# barrier arrival waits only for the arrival atomic (vmcnt(1)); the early L1 invalidate completes in the shadow of the write-back / polling
# speedup vs baseline: 1.0083x; 1.0083x over previous
.LBB0_238:
	s_or_b64 exec, exec, s[16:17]
	v_cvt_f32_u32_e32 v4, v2
	buffer_inv sc1
	s_waitcnt vmcnt(1)
	v_readfirstlane_b32 s3, v3
	v_sub_u32_e32 v3, 0, v2
	v_rcp_iflag_f32_e32 v4, v4
	v_add_u32_e32 v5, s3, v1
	v_mul_f32_e32 v4, 0x4f7ffffe, v4
	v_cvt_u32_f32_e32 v4, v4
	v_mul_lo_u32 v1, v3, v4
	v_mul_hi_u32 v1, v4, v1
	v_add_u32_e32 v1, v4, v1
	v_mul_hi_u32 v1, v5, v1
	v_mul_lo_u32 v3, v1, v2
	v_sub_u32_e32 v3, v5, v3
	v_add_u32_e32 v4, 1, v1
	v_cmp_ge_u32_e32 vcc, v3, v2
	s_nop 1
	v_cndmask_b32_e32 v1, v1, v4, vcc
	v_sub_u32_e32 v4, v3, v2
	v_cndmask_b32_e32 v3, v3, v4, vcc
	v_add_u32_e32 v4, 1, v1
	v_cmp_ge_u32_e32 vcc, v3, v2
	v_add_u32_e32 v3, 1, v5
	s_nop 0
	v_cndmask_b32_e32 v1, v1, v4, vcc
	v_mul_lo_u32 v4, v2, v1
	v_add_u32_e32 v2, v4, v2
	v_cmp_ne_u32_e32 vcc, v3, v2
	s_and_saveexec_b64 s[14:15], vcc
	s_xor_b64 s[14:15], exec, s[14:15]
	s_cbranch_execz .LBB0_252
	s_waitcnt lgkmcnt(0)
	v_mov_b32_e32 v0, 0x2000
	global_load_dword v0, v0, s[12:13] offset:1024 sc1
	s_add_u32 s18, s12, 0x2400
	s_addc_u32 s19, s13, 0
	s_waitcnt vmcnt(0)
	v_cmp_eq_u32_e32 vcc, v0, v1
	s_and_saveexec_b64 s[16:17], vcc
	s_cbranch_execz .LBB0_251
	s_mov_b32 s3, 1
	s_mov_b64 s[20:21], 0
	v_mov_b32_e32 v0, 0
	s_branch .LBB0_242

.LBB0_514:
	s_or_b64 exec, exec, s[12:13]
	v_cvt_f32_u32_e32 v4, v2
	buffer_inv sc1
	s_waitcnt vmcnt(1)
	v_readfirstlane_b32 s3, v3
	v_sub_u32_e32 v3, 0, v2
	v_rcp_iflag_f32_e32 v4, v4
	v_add_u32_e32 v5, s3, v1
	v_mul_f32_e32 v4, 0x4f7ffffe, v4
	v_cvt_u32_f32_e32 v4, v4
	v_mul_lo_u32 v1, v3, v4
	v_mul_hi_u32 v1, v4, v1
	v_add_u32_e32 v1, v4, v1
	v_mul_hi_u32 v1, v5, v1
	v_mul_lo_u32 v3, v1, v2
	v_sub_u32_e32 v3, v5, v3
	v_add_u32_e32 v4, 1, v1
	v_cmp_ge_u32_e32 vcc, v3, v2
	s_nop 1
	v_cndmask_b32_e32 v1, v1, v4, vcc
	v_sub_u32_e32 v4, v3, v2
	v_cndmask_b32_e32 v3, v3, v4, vcc
	v_add_u32_e32 v4, 1, v1
	v_cmp_ge_u32_e32 vcc, v3, v2
	v_add_u32_e32 v3, 1, v5
	s_nop 0
	v_cndmask_b32_e32 v1, v1, v4, vcc
	v_mul_lo_u32 v4, v2, v1
	v_add_u32_e32 v2, v4, v2
	v_cmp_ne_u32_e32 vcc, v3, v2
	s_and_saveexec_b64 s[10:11], vcc
	s_xor_b64 s[10:11], exec, s[10:11]
	s_cbranch_execz .LBB0_528
	s_waitcnt lgkmcnt(0)
	v_mov_b32_e32 v0, 0x2000
	global_load_dword v0, v0, s[8:9] offset:1024 sc1
	s_add_u32 s14, s8, 0x2400
	s_addc_u32 s15, s9, 0
	s_waitcnt vmcnt(0)
	v_cmp_eq_u32_e32 vcc, v0, v1
	s_and_saveexec_b64 s[12:13], vcc
	s_cbranch_execz .LBB0_527
	s_mov_b32 s3, 1
	s_mov_b64 s[16:17], 0
	v_mov_b32_e32 v0, 0
	s_branch .LBB0_518
